# router: first 16 of 36 weight columns cached in LDS once per workgroup (LDS is idle in this phase) and read with ds_read_b128; remaining columns from global as before
# speedup vs baseline: 1.0417x; 1.0029x over previous
; #define PIN(i) (*(const float* const __attribute__((address_space(4)))*)(KA + 8 * (i)))
; DEVI void phase_p7(const int TIDX, const int BIDX, const int GDIM, KAP KA, unsigned char* WSB, float* OUTB, int l, unsigned char* smem) {
;   const int tid = TIDX, lane = tid & 63;
;   {
;     const float* PRE = (const float*)(WSB + O_PRE);
;     bf16_t* XB = (bf16_t*)(WSB + O_XB);
;     const float* WR = (const float*)(WSB + O_WR) + (size_t)l * 36 * 1024;
;     int* cnt = (int*)(WSB + O_CNT) + 1024 + l * 1024;
;     int* ltok = (int*)(WSB + O_LTOK);
;     float* lw = (float*)(WSB + O_LW);
;     const float* g1 = PIN(I_LN1G) + l * 1024; const float* b1 = PIN(I_LN1B) + l * 1024;
;     const int wid = BIDX * 4 + (tid >> 6), nw = GDIM * 4;
;     for (int r4 = wid; r4 < NTOK / 4; r4 += nw) {
;       float4 v[4][4];
; #pragma unroll
;       for (int t = 0; t < 4; ++t) {
;         const size_t row = (size_t)r4 * 4 + t;
; #pragma unroll
;         for (int j = 0; j < 4; ++j) v[t][j] = resid_plus(*(const uint2*)(XB + row * 1024 + j * 256 + lane * 4), *(const uint2*)((const bf16_t*)PRE + row * 1024 + j * 256 + lane * 4));
;         ln_inplace(v[t], g1, b1, lane);
;         store_row(v[t], OUTB + row * 1024, XB + row * 1024, lane);
;       }
;       float mine[4] = {0.f, 0.f, 0.f, 0.f};
; #pragma unroll 4
;       for (int c = 0; c < 36; ++c) {
;         float4 wv[4];
; #pragma unroll
;         for (int j = 0; j < 4; ++j) wv[j] = *(const float4*)(WR + c * 1024 + j * 256 + lane * 4);
.LBB0_65:
	v_readlane_b32 s0, v255, 13
	v_readlane_b32 s1, v255, 14
	s_ashr_i32 s1, s0, 31
	v_writelane_b32 v255, s0, 13
	v_ashrrev_i32_e32 v0, 6, v130
	v_lshl_add_u32 v32, s92, 2, v0
	v_writelane_b32 v255, s1, 14
	s_movk_i32 s0, 0x4080
	v_cmp_gt_i32_e32 vcc, s0, v32
	s_and_saveexec_b64 s[74:75], vcc
	s_cbranch_execz .LBB0_88
	v_readlane_b32 s6, v255, 13
	s_lshl_b32 s0, s6, 10
	s_ashr_i32 s1, s0, 31
	s_lshl_b64 s[4:5], s[0:1], 2
	s_waitcnt lgkmcnt(0)
	s_add_u32 s0, s50, s4
	s_addc_u32 s1, s51, s5
	s_add_u32 s44, s0, 0x22aa000
	s_addc_u32 s45, s1, 0
	s_load_dwordx4 s[0:3], s[88:89], 0xa0
	s_add_u32 s46, s50, 0xa3ad800
	s_addc_u32 s47, s51, 0
	s_add_u32 s40, s50, 0xabbd800
	s_addc_u32 s41, s51, 0
	s_lshl_b32 s42, s84, 2
	s_waitcnt lgkmcnt(0)
	s_add_u32 s2, s2, s4
	v_and_b32_e32 v45, 63, v130
	s_addc_u32 s3, s3, s5
	s_add_u32 s0, s0, s4
	v_lshlrev_b32_e32 v128, 3, v45
	s_addc_u32 s1, s1, s5
	v_lshl_add_u64 v[0:1], s[50:51], 0, v[128:129]
	s_mov_b64 s[4:5], 0x22ad000
	s_mul_i32 s23, s6, 0x24000
	v_lshl_add_u64 v[34:35], v[0:1], 0, s[4:5]
	s_mov_b64 s[4:5], 0xbbed800
	v_lshlrev_b32_e32 v128, 4, v45
	s_mul_hi_i32 s22, s6, 0x24000
	v_lshl_add_u64 v[36:37], v[0:1], 0, s[4:5]
	v_lshl_add_u64 v[38:39], s[0:1], 0, v[128:129]
	v_and_b32_e32 v0, 64, v161
	s_add_u32 s0, s50, s23
	v_readlane_b32 s7, v255, 14
	v_lshlrev_b32_e32 v85, 2, v0
	s_addc_u32 s1, s51, s22
	v_lshl_add_u64 v[40:41], s[2:3], 0, v[128:129]
	v_or_b32_e32 v84, 4, v0
	v_cmp_gt_u32_e64 s[4:5], 8, v45
	v_or_b32_e32 v86, 4, v85
	v_or_b32_e32 v87, 8, v85
	v_or_b32_e32 v88, 12, v85
	v_cmp_eq_u32_e64 s[6:7], 0, v45
	v_cmp_eq_u32_e64 s[8:9], 1, v45
	v_cmp_eq_u32_e64 s[10:11], 2, v45
	v_cmp_eq_u32_e64 s[12:13], 3, v45
	v_cmp_eq_u32_e64 s[14:15], 4, v45
	v_cmp_eq_u32_e64 s[16:17], 5, v45
	v_cmp_eq_u32_e64 s[18:19], 6, v45
	v_cmp_eq_u32_e64 s[20:21], 7, v45
	v_lshl_add_u64 v[42:43], s[0:1], 0, v[128:129]
	v_and_b32_e32 v204, 0xffffffc0, v130
	v_lshlrev_b32_e32 v204, 4, v204
	v_mov_b32_e32 v205, 0
	v_lshl_add_u64 v[204:205], v[42:43], 0, v[204:205]
	s_mov_b64 s[22:23], 0x2220000
	s_mov_b64 s[24:25], 0x1000
	v_lshl_add_u64 v[204:205], v[204:205], 0, s[22:23]
	v_lshlrev_b32_e32 v208, 4, v130
	global_load_dwordx4 v[142:145], v[204:205], off
	v_lshl_add_u64 v[204:205], v[204:205], 0, s[24:25]
	global_load_dwordx4 v[146:149], v[204:205], off
	v_lshl_add_u64 v[204:205], v[204:205], 0, s[24:25]
	global_load_dwordx4 v[150:153], v[204:205], off
	v_lshl_add_u64 v[204:205], v[204:205], 0, s[24:25]
	global_load_dwordx4 v[154:157], v[204:205], off
	v_lshl_add_u64 v[204:205], v[204:205], 0, s[24:25]
	global_load_dwordx4 v[162:165], v[204:205], off
	v_lshl_add_u64 v[204:205], v[204:205], 0, s[24:25]
	global_load_dwordx4 v[166:169], v[204:205], off
	v_lshl_add_u64 v[204:205], v[204:205], 0, s[24:25]
	global_load_dwordx4 v[170:173], v[204:205], off
	v_lshl_add_u64 v[204:205], v[204:205], 0, s[24:25]
	global_load_dwordx4 v[174:177], v[204:205], off
	v_lshl_add_u64 v[204:205], v[204:205], 0, s[24:25]
	global_load_dwordx4 v[178:181], v[204:205], off
	v_lshl_add_u64 v[204:205], v[204:205], 0, s[24:25]
	global_load_dwordx4 v[182:185], v[204:205], off
	v_lshl_add_u64 v[204:205], v[204:205], 0, s[24:25]
	global_load_dwordx4 v[186:189], v[204:205], off
	v_lshl_add_u64 v[204:205], v[204:205], 0, s[24:25]
	global_load_dwordx4 v[190:193], v[204:205], off
	v_lshl_add_u64 v[204:205], v[204:205], 0, s[24:25]
	global_load_dwordx4 v[196:199], v[204:205], off
	v_lshl_add_u64 v[204:205], v[204:205], 0, s[24:25]
	global_load_dwordx4 v[200:203], v[204:205], off
	v_lshl_add_u64 v[204:205], v[204:205], 0, s[24:25]
	global_load_dwordx4 v[236:239], v[204:205], off
	v_lshl_add_u64 v[204:205], v[204:205], 0, s[24:25]
	global_load_dwordx4 v[240:243], v[204:205], off
	v_lshl_add_u64 v[204:205], v[204:205], 0, s[24:25]
	s_waitcnt vmcnt(0)
	ds_write_b128 v208, v[142:145]
	ds_write_b128 v208, v[146:149] offset:4096
	ds_write_b128 v208, v[150:153] offset:8192
	ds_write_b128 v208, v[154:157] offset:12288
	ds_write_b128 v208, v[162:165] offset:16384
	ds_write_b128 v208, v[166:169] offset:20480
	ds_write_b128 v208, v[170:173] offset:24576
	ds_write_b128 v208, v[174:177] offset:28672
	ds_write_b128 v208, v[178:181] offset:32768
	ds_write_b128 v208, v[182:185] offset:36864
	ds_write_b128 v208, v[186:189] offset:40960
	ds_write_b128 v208, v[190:193] offset:45056
	ds_write_b128 v208, v[196:199] offset:49152
	ds_write_b128 v208, v[200:203] offset:53248
	ds_write_b128 v208, v[236:239] offset:57344
	ds_write_b128 v208, v[240:243] offset:61440
	s_waitcnt lgkmcnt(0)
	s_barrier
	v_lshlrev_b32_e32 v44, 12, v45
	s_mov_b64 s[38:39], 0
	s_branch .LBB0_68

; DEVI void phase_p7(const int TIDX, const int BIDX, const int GDIM, KAP KA, unsigned char* WSB, float* OUTB, int l, unsigned char* smem) {
;     ...
; #pragma unroll 4
;       for (int c = 0; c < 36; ++c) {
;         float4 wv[4];
; #pragma unroll
;         for (int j = 0; j < 4; ++j) wv[j] = *(const float4*)(WR + c * 1024 + j * 256 + lane * 4);
; #pragma unroll
;         for (int t = 0; t < 4; ++t) {
;           float s = 0.f;
; #pragma unroll
;           for (int j = 0; j < 4; ++j) s += v[t][j].x * wv[j].x + v[t][j].y * wv[j].y + v[t][j].z * wv[j].z + v[t][j].w * wv[j].w;
;           s = wave_sum(s);
;           if (lane == c) mine[t] = s;
.LBB0_69:
	s_cmp_lt_u32 s2, 16
	s_cbranch_scc0 .Lr_glob
	v_lshl_add_u32 v209, v45, 4, s0
	ds_read_b128 v[142:145], v209
	ds_read_b128 v[146:149], v209 offset:1024
	ds_read_b128 v[150:153], v209 offset:2048
	ds_read_b128 v[154:157], v209 offset:3072
	ds_read_b128 v[162:165], v209 offset:4096
	ds_read_b128 v[166:169], v209 offset:5120
	ds_read_b128 v[170:173], v209 offset:6144
	ds_read_b128 v[174:177], v209 offset:7168
	ds_read_b128 v[178:181], v209 offset:8192
	ds_read_b128 v[182:185], v209 offset:9216
	ds_read_b128 v[186:189], v209 offset:10240
	ds_read_b128 v[190:193], v209 offset:11264
	ds_read_b128 v[196:199], v209 offset:12288
	ds_read_b128 v[200:203], v209 offset:13312
	ds_read_b128 v[236:239], v209 offset:14336
	ds_read_b128 v[240:243], v209 offset:15360
	s_waitcnt lgkmcnt(14)
	v_pk_mul_f32 v[244:245], v[26:27], v[142:143] op_sel:[0,1] op_sel_hi:[1,1]
	v_pk_mul_f32 v[246:247], v[4:5], v[142:143] op_sel:[0,1] op_sel_hi:[1,1]
	v_pk_mul_f32 v[248:249], v[56:57], v[146:147] op_sel:[0,1] op_sel_hi:[1,1]
	v_pk_mul_f32 v[250:251], v[20:21], v[146:147] op_sel:[0,1] op_sel_hi:[1,1]
	v_pk_fma_f32 v[244:245], v[24:25], v[142:143], v[244:245] op_sel:[0,0,0] op_sel_hi:[1,0,1]
	v_pk_fma_f32 v[246:247], v[16:17], v[142:143], v[246:247] op_sel:[0,0,0] op_sel_hi:[1,0,1]
	v_pk_fma_f32 v[248:249], v[54:55], v[146:147], v[248:249] op_sel:[0,0,0] op_sel_hi:[1,0,1]
	v_pk_fma_f32 v[250:251], v[14:15], v[146:147], v[250:251] op_sel:[0,0,0] op_sel_hi:[1,0,1]
	v_pk_fma_f32 v[244:245], v[28:29], v[144:145], v[244:245] op_sel:[0,0,0] op_sel_hi:[1,0,1]
	v_pk_fma_f32 v[246:247], v[18:19], v[144:145], v[246:247] op_sel:[0,0,0] op_sel_hi:[1,0,1]
	v_pk_fma_f32 v[248:249], v[58:59], v[148:149], v[248:249] op_sel:[0,0,0] op_sel_hi:[1,0,1]
	v_pk_fma_f32 v[250:251], v[22:23], v[148:149], v[250:251] op_sel:[0,0,0] op_sel_hi:[1,0,1]
	v_pk_fma_f32 v[244:245], v[30:31], v[144:145], v[244:245] op_sel:[0,1,0] op_sel_hi:[1,1,1]
	v_pk_fma_f32 v[246:247], v[2:3], v[144:145], v[246:247] op_sel:[0,1,0] op_sel_hi:[1,1,1]
	v_pk_fma_f32 v[248:249], v[60:61], v[148:149], v[248:249] op_sel:[0,1,0] op_sel_hi:[1,1,1]
	v_pk_fma_f32 v[250:251], v[70:71], v[148:149], v[250:251] op_sel:[0,1,0] op_sel_hi:[1,1,1]
	v_pk_add_f32 v[252:253], v[244:245], 0
	v_pk_add_f32 v[158:159], v[246:247], 0
	v_pk_add_f32 v[252:253], v[252:253], v[248:249]
	v_pk_add_f32 v[158:159], v[158:159], v[250:251]
	s_waitcnt lgkmcnt(12)
	v_pk_mul_f32 v[244:245], v[48:49], v[150:151] op_sel:[0,1] op_sel_hi:[1,1]
	v_pk_mul_f32 v[246:247], v[8:9], v[150:151] op_sel:[0,1] op_sel_hi:[1,1]
	v_pk_mul_f32 v[248:249], v[64:65], v[154:155] op_sel:[0,1] op_sel_hi:[1,1]
	v_pk_mul_f32 v[250:251], v[74:75], v[154:155] op_sel:[0,1] op_sel_hi:[1,1]
	v_pk_fma_f32 v[244:245], v[46:47], v[150:151], v[244:245] op_sel:[0,0,0] op_sel_hi:[1,0,1]
	v_pk_fma_f32 v[246:247], v[6:7], v[150:151], v[246:247] op_sel:[0,0,0] op_sel_hi:[1,0,1]
	v_pk_fma_f32 v[248:249], v[62:63], v[154:155], v[248:249] op_sel:[0,0,0] op_sel_hi:[1,0,1]
	v_pk_fma_f32 v[250:251], v[72:73], v[154:155], v[250:251] op_sel:[0,0,0] op_sel_hi:[1,0,1]
	v_pk_fma_f32 v[244:245], v[50:51], v[152:153], v[244:245] op_sel:[0,0,0] op_sel_hi:[1,0,1]
	v_pk_fma_f32 v[246:247], v[12:13], v[152:153], v[246:247] op_sel:[0,0,0] op_sel_hi:[1,0,1]
	v_pk_fma_f32 v[248:249], v[66:67], v[156:157], v[248:249] op_sel:[0,0,0] op_sel_hi:[1,0,1]
	v_pk_fma_f32 v[250:251], v[76:77], v[156:157], v[250:251] op_sel:[0,0,0] op_sel_hi:[1,0,1]
	v_pk_fma_f32 v[244:245], v[52:53], v[152:153], v[244:245] op_sel:[0,1,0] op_sel_hi:[1,1,1]
	v_pk_fma_f32 v[246:247], v[10:11], v[152:153], v[246:247] op_sel:[0,1,0] op_sel_hi:[1,1,1]
	v_pk_fma_f32 v[248:249], v[68:69], v[156:157], v[248:249] op_sel:[0,1,0] op_sel_hi:[1,1,1]
	v_pk_fma_f32 v[250:251], v[78:79], v[156:157], v[250:251] op_sel:[0,1,0] op_sel_hi:[1,1,1]
	v_pk_add_f32 v[252:253], v[252:253], v[244:245]
	v_pk_add_f32 v[158:159], v[158:159], v[246:247]
	v_pk_add_f32 v[252:253], v[252:253], v[248:249]
	v_pk_add_f32 v[158:159], v[158:159], v[250:251]
	s_mov_b32 m0, s2
	s_nop 0
	v_add_f32_dpp v252, v252, v252 quad_perm:[1,0,3,2] row_mask:0xf bank_mask:0xf bound_ctrl:1
	v_add_f32_dpp v253, v253, v253 quad_perm:[1,0,3,2] row_mask:0xf bank_mask:0xf bound_ctrl:1
	v_add_f32_dpp v158, v158, v158 quad_perm:[1,0,3,2] row_mask:0xf bank_mask:0xf bound_ctrl:1
	v_add_f32_dpp v159, v159, v159 quad_perm:[1,0,3,2] row_mask:0xf bank_mask:0xf bound_ctrl:1
	v_add_f32_dpp v252, v252, v252 quad_perm:[2,3,0,1] row_mask:0xf bank_mask:0xf bound_ctrl:1
	v_add_f32_dpp v253, v253, v253 quad_perm:[2,3,0,1] row_mask:0xf bank_mask:0xf bound_ctrl:1
	v_add_f32_dpp v158, v158, v158 quad_perm:[2,3,0,1] row_mask:0xf bank_mask:0xf bound_ctrl:1
	v_add_f32_dpp v159, v159, v159 quad_perm:[2,3,0,1] row_mask:0xf bank_mask:0xf bound_ctrl:1
	v_add_f32_dpp v252, v252, v252 row_half_mirror row_mask:0xf bank_mask:0xf bound_ctrl:1
	v_add_f32_dpp v253, v253, v253 row_half_mirror row_mask:0xf bank_mask:0xf bound_ctrl:1
	v_add_f32_dpp v158, v158, v158 row_half_mirror row_mask:0xf bank_mask:0xf bound_ctrl:1
	v_add_f32_dpp v159, v159, v159 row_half_mirror row_mask:0xf bank_mask:0xf bound_ctrl:1
	v_add_f32_dpp v252, v252, v252 row_mirror row_mask:0xf bank_mask:0xf bound_ctrl:1
	v_add_f32_dpp v253, v253, v253 row_mirror row_mask:0xf bank_mask:0xf bound_ctrl:1
	v_add_f32_dpp v158, v158, v158 row_mirror row_mask:0xf bank_mask:0xf bound_ctrl:1
	v_add_f32_dpp v159, v159, v159 row_mirror row_mask:0xf bank_mask:0xf bound_ctrl:1
	v_mov_b32_e32 v94, v252
	s_waitcnt lgkmcnt(10)
; DEVI void phase_p7(const int TIDX, const int BIDX, const int GDIM, KAP KA, unsigned char* WSB, float* OUTB, int l, unsigned char* smem) {
;     ...
; #pragma unroll 4
;       for (int c = 0; c < 36; ++c) {
;         float4 wv[4];
; #pragma unroll
;         for (int j = 0; j < 4; ++j) wv[j] = *(const float4*)(WR + c * 1024 + j * 256 + lane * 4);
; #pragma unroll
;         for (int t = 0; t < 4; ++t) {
;           float s = 0.f;
; #pragma unroll
;           for (int j = 0; j < 4; ++j) s += v[t][j].x * wv[j].x + v[t][j].y * wv[j].y + v[t][j].z * wv[j].z + v[t][j].w * wv[j].w;
;           s = wave_sum(s);
;           if (lane == c) mine[t] = s;
	v_pk_mul_f32 v[244:245], v[26:27], v[162:163] op_sel:[0,1] op_sel_hi:[1,1]
	v_mov_b32_dpp v94, v253 row_shr:4 row_mask:0xf bank_mask:0x2
	v_pk_mul_f32 v[246:247], v[4:5], v[162:163] op_sel:[0,1] op_sel_hi:[1,1]
	v_pk_mul_f32 v[248:249], v[56:57], v[166:167] op_sel:[0,1] op_sel_hi:[1,1]
	v_mov_b32_dpp v94, v158 row_shr:8 row_mask:0xf bank_mask:0x4
	v_pk_mul_f32 v[250:251], v[20:21], v[166:167] op_sel:[0,1] op_sel_hi:[1,1]
	v_pk_fma_f32 v[244:245], v[24:25], v[162:163], v[244:245] op_sel:[0,0,0] op_sel_hi:[1,0,1]
	v_mov_b32_dpp v94, v159 row_shr:12 row_mask:0xf bank_mask:0x8
	v_mov_b32_e32 v95, v94
	v_pk_fma_f32 v[246:247], v[16:17], v[162:163], v[246:247] op_sel:[0,0,0] op_sel_hi:[1,0,1]
	v_pk_fma_f32 v[248:249], v[54:55], v[166:167], v[248:249] op_sel:[0,0,0] op_sel_hi:[1,0,1]
	v_permlane16_swap_b32_e32 v94, v95
	v_pk_fma_f32 v[250:251], v[14:15], v[166:167], v[250:251] op_sel:[0,0,0] op_sel_hi:[1,0,1]
	v_add_f32_e32 v96, v94, v95
	v_mov_b32_e32 v97, v96
	v_pk_fma_f32 v[244:245], v[28:29], v[164:165], v[244:245] op_sel:[0,0,0] op_sel_hi:[1,0,1]
	v_pk_fma_f32 v[246:247], v[18:19], v[164:165], v[246:247] op_sel:[0,0,0] op_sel_hi:[1,0,1]
	v_permlane32_swap_b32_e32 v96, v97
	v_pk_fma_f32 v[248:249], v[58:59], v[168:169], v[248:249] op_sel:[0,0,0] op_sel_hi:[1,0,1]
	v_add_f32_e32 v98, v96, v97
	v_pk_fma_f32 v[250:251], v[22:23], v[168:169], v[250:251] op_sel:[0,0,0] op_sel_hi:[1,0,1]
	v_readlane_b32 s24, v98, 0
	v_readlane_b32 s25, v98, 4
	v_readlane_b32 s26, v98, 8
	v_readlane_b32 s27, v98, 12
	v_writelane_b32 v82, s24, m0
	v_writelane_b32 v33, s25, m0
	v_writelane_b32 v0, s26, m0
	v_writelane_b32 v1, s27, m0
	v_pk_fma_f32 v[244:245], v[30:31], v[164:165], v[244:245] op_sel:[0,1,0] op_sel_hi:[1,1,1]
	v_pk_fma_f32 v[246:247], v[2:3], v[164:165], v[246:247] op_sel:[0,1,0] op_sel_hi:[1,1,1]
	v_pk_fma_f32 v[248:249], v[60:61], v[168:169], v[248:249] op_sel:[0,1,0] op_sel_hi:[1,1,1]
	v_pk_fma_f32 v[250:251], v[70:71], v[168:169], v[250:251] op_sel:[0,1,0] op_sel_hi:[1,1,1]
	v_pk_add_f32 v[252:253], v[244:245], 0
	v_pk_add_f32 v[158:159], v[246:247], 0
	v_pk_add_f32 v[252:253], v[252:253], v[248:249]
	v_pk_add_f32 v[158:159], v[158:159], v[250:251]
	s_waitcnt lgkmcnt(8)
	v_pk_mul_f32 v[244:245], v[48:49], v[170:171] op_sel:[0,1] op_sel_hi:[1,1]
	v_pk_mul_f32 v[246:247], v[8:9], v[170:171] op_sel:[0,1] op_sel_hi:[1,1]
	v_pk_mul_f32 v[248:249], v[64:65], v[174:175] op_sel:[0,1] op_sel_hi:[1,1]
	v_pk_mul_f32 v[250:251], v[74:75], v[174:175] op_sel:[0,1] op_sel_hi:[1,1]
	v_pk_fma_f32 v[244:245], v[46:47], v[170:171], v[244:245] op_sel:[0,0,0] op_sel_hi:[1,0,1]
	v_pk_fma_f32 v[246:247], v[6:7], v[170:171], v[246:247] op_sel:[0,0,0] op_sel_hi:[1,0,1]
	v_pk_fma_f32 v[248:249], v[62:63], v[174:175], v[248:249] op_sel:[0,0,0] op_sel_hi:[1,0,1]
	v_pk_fma_f32 v[250:251], v[72:73], v[174:175], v[250:251] op_sel:[0,0,0] op_sel_hi:[1,0,1]
	v_pk_fma_f32 v[244:245], v[50:51], v[172:173], v[244:245] op_sel:[0,0,0] op_sel_hi:[1,0,1]
	v_pk_fma_f32 v[246:247], v[12:13], v[172:173], v[246:247] op_sel:[0,0,0] op_sel_hi:[1,0,1]
	v_pk_fma_f32 v[248:249], v[66:67], v[176:177], v[248:249] op_sel:[0,0,0] op_sel_hi:[1,0,1]
	v_pk_fma_f32 v[250:251], v[76:77], v[176:177], v[250:251] op_sel:[0,0,0] op_sel_hi:[1,0,1]
	v_pk_fma_f32 v[244:245], v[52:53], v[172:173], v[244:245] op_sel:[0,1,0] op_sel_hi:[1,1,1]
	v_pk_fma_f32 v[246:247], v[10:11], v[172:173], v[246:247] op_sel:[0,1,0] op_sel_hi:[1,1,1]
	v_pk_fma_f32 v[248:249], v[68:69], v[176:177], v[248:249] op_sel:[0,1,0] op_sel_hi:[1,1,1]
	v_pk_fma_f32 v[250:251], v[78:79], v[176:177], v[250:251] op_sel:[0,1,0] op_sel_hi:[1,1,1]
	v_pk_add_f32 v[252:253], v[252:253], v[244:245]
	v_pk_add_f32 v[158:159], v[158:159], v[246:247]
	v_pk_add_f32 v[252:253], v[252:253], v[248:249]
	v_pk_add_f32 v[158:159], v[158:159], v[250:251]
	s_or_b32 s101, s2, 1
	s_mov_b32 m0, s101
	v_add_f32_dpp v252, v252, v252 quad_perm:[1,0,3,2] row_mask:0xf bank_mask:0xf bound_ctrl:1
	v_add_f32_dpp v253, v253, v253 quad_perm:[1,0,3,2] row_mask:0xf bank_mask:0xf bound_ctrl:1
	v_add_f32_dpp v158, v158, v158 quad_perm:[1,0,3,2] row_mask:0xf bank_mask:0xf bound_ctrl:1
	v_add_f32_dpp v159, v159, v159 quad_perm:[1,0,3,2] row_mask:0xf bank_mask:0xf bound_ctrl:1
	v_add_f32_dpp v252, v252, v252 quad_perm:[2,3,0,1] row_mask:0xf bank_mask:0xf bound_ctrl:1
	v_add_f32_dpp v253, v253, v253 quad_perm:[2,3,0,1] row_mask:0xf bank_mask:0xf bound_ctrl:1
	v_add_f32_dpp v158, v158, v158 quad_perm:[2,3,0,1] row_mask:0xf bank_mask:0xf bound_ctrl:1
	v_add_f32_dpp v159, v159, v159 quad_perm:[2,3,0,1] row_mask:0xf bank_mask:0xf bound_ctrl:1
	v_add_f32_dpp v252, v252, v252 row_half_mirror row_mask:0xf bank_mask:0xf bound_ctrl:1
	v_add_f32_dpp v253, v253, v253 row_half_mirror row_mask:0xf bank_mask:0xf bound_ctrl:1
	v_add_f32_dpp v158, v158, v158 row_half_mirror row_mask:0xf bank_mask:0xf bound_ctrl:1
	v_add_f32_dpp v159, v159, v159 row_half_mirror row_mask:0xf bank_mask:0xf bound_ctrl:1
	v_add_f32_dpp v252, v252, v252 row_mirror row_mask:0xf bank_mask:0xf bound_ctrl:1
	v_add_f32_dpp v253, v253, v253 row_mirror row_mask:0xf bank_mask:0xf bound_ctrl:1
	v_add_f32_dpp v158, v158, v158 row_mirror row_mask:0xf bank_mask:0xf bound_ctrl:1
	v_add_f32_dpp v159, v159, v159 row_mirror row_mask:0xf bank_mask:0xf bound_ctrl:1
	v_mov_b32_e32 v94, v252
	s_waitcnt lgkmcnt(6)
; DEVI void phase_p7(const int TIDX, const int BIDX, const int GDIM, KAP KA, unsigned char* WSB, float* OUTB, int l, unsigned char* smem) {
;     ...
; #pragma unroll 4
;       for (int c = 0; c < 36; ++c) {
;         float4 wv[4];
; #pragma unroll
;         for (int j = 0; j < 4; ++j) wv[j] = *(const float4*)(WR + c * 1024 + j * 256 + lane * 4);
; #pragma unroll
;         for (int t = 0; t < 4; ++t) {
;           float s = 0.f;
; #pragma unroll
;           for (int j = 0; j < 4; ++j) s += v[t][j].x * wv[j].x + v[t][j].y * wv[j].y + v[t][j].z * wv[j].z + v[t][j].w * wv[j].w;
;           s = wave_sum(s);
;           if (lane == c) mine[t] = s;
	v_pk_mul_f32 v[244:245], v[26:27], v[178:179] op_sel:[0,1] op_sel_hi:[1,1]
	v_mov_b32_dpp v94, v253 row_shr:4 row_mask:0xf bank_mask:0x2
	v_pk_mul_f32 v[246:247], v[4:5], v[178:179] op_sel:[0,1] op_sel_hi:[1,1]
	v_pk_mul_f32 v[248:249], v[56:57], v[182:183] op_sel:[0,1] op_sel_hi:[1,1]
	v_mov_b32_dpp v94, v158 row_shr:8 row_mask:0xf bank_mask:0x4
	v_pk_mul_f32 v[250:251], v[20:21], v[182:183] op_sel:[0,1] op_sel_hi:[1,1]
	v_pk_fma_f32 v[244:245], v[24:25], v[178:179], v[244:245] op_sel:[0,0,0] op_sel_hi:[1,0,1]
	v_mov_b32_dpp v94, v159 row_shr:12 row_mask:0xf bank_mask:0x8
	v_mov_b32_e32 v95, v94
	v_pk_fma_f32 v[246:247], v[16:17], v[178:179], v[246:247] op_sel:[0,0,0] op_sel_hi:[1,0,1]
	v_pk_fma_f32 v[248:249], v[54:55], v[182:183], v[248:249] op_sel:[0,0,0] op_sel_hi:[1,0,1]
	v_permlane16_swap_b32_e32 v94, v95
	v_pk_fma_f32 v[250:251], v[14:15], v[182:183], v[250:251] op_sel:[0,0,0] op_sel_hi:[1,0,1]
	v_add_f32_e32 v96, v94, v95
	v_mov_b32_e32 v97, v96
	v_pk_fma_f32 v[244:245], v[28:29], v[180:181], v[244:245] op_sel:[0,0,0] op_sel_hi:[1,0,1]
	v_pk_fma_f32 v[246:247], v[18:19], v[180:181], v[246:247] op_sel:[0,0,0] op_sel_hi:[1,0,1]
	v_permlane32_swap_b32_e32 v96, v97
	v_pk_fma_f32 v[248:249], v[58:59], v[184:185], v[248:249] op_sel:[0,0,0] op_sel_hi:[1,0,1]
	v_add_f32_e32 v98, v96, v97
	v_pk_fma_f32 v[250:251], v[22:23], v[184:185], v[250:251] op_sel:[0,0,0] op_sel_hi:[1,0,1]
	v_readlane_b32 s24, v98, 0
	v_readlane_b32 s25, v98, 4
	v_readlane_b32 s26, v98, 8
	v_readlane_b32 s27, v98, 12
	v_writelane_b32 v82, s24, m0
	v_writelane_b32 v33, s25, m0
	v_writelane_b32 v0, s26, m0
	v_writelane_b32 v1, s27, m0
	v_pk_fma_f32 v[244:245], v[30:31], v[180:181], v[244:245] op_sel:[0,1,0] op_sel_hi:[1,1,1]
	v_pk_fma_f32 v[246:247], v[2:3], v[180:181], v[246:247] op_sel:[0,1,0] op_sel_hi:[1,1,1]
	v_pk_fma_f32 v[248:249], v[60:61], v[184:185], v[248:249] op_sel:[0,1,0] op_sel_hi:[1,1,1]
	v_pk_fma_f32 v[250:251], v[70:71], v[184:185], v[250:251] op_sel:[0,1,0] op_sel_hi:[1,1,1]
	v_pk_add_f32 v[252:253], v[244:245], 0
	v_pk_add_f32 v[158:159], v[246:247], 0
	v_pk_add_f32 v[252:253], v[252:253], v[248:249]
	v_pk_add_f32 v[158:159], v[158:159], v[250:251]
	s_waitcnt lgkmcnt(4)
	v_pk_mul_f32 v[244:245], v[48:49], v[186:187] op_sel:[0,1] op_sel_hi:[1,1]
	v_pk_mul_f32 v[246:247], v[8:9], v[186:187] op_sel:[0,1] op_sel_hi:[1,1]
	v_pk_mul_f32 v[248:249], v[64:65], v[190:191] op_sel:[0,1] op_sel_hi:[1,1]
	v_pk_mul_f32 v[250:251], v[74:75], v[190:191] op_sel:[0,1] op_sel_hi:[1,1]
	v_pk_fma_f32 v[244:245], v[46:47], v[186:187], v[244:245] op_sel:[0,0,0] op_sel_hi:[1,0,1]
	v_pk_fma_f32 v[246:247], v[6:7], v[186:187], v[246:247] op_sel:[0,0,0] op_sel_hi:[1,0,1]
	v_pk_fma_f32 v[248:249], v[62:63], v[190:191], v[248:249] op_sel:[0,0,0] op_sel_hi:[1,0,1]
	v_pk_fma_f32 v[250:251], v[72:73], v[190:191], v[250:251] op_sel:[0,0,0] op_sel_hi:[1,0,1]
	v_pk_fma_f32 v[244:245], v[50:51], v[188:189], v[244:245] op_sel:[0,0,0] op_sel_hi:[1,0,1]
	v_pk_fma_f32 v[246:247], v[12:13], v[188:189], v[246:247] op_sel:[0,0,0] op_sel_hi:[1,0,1]
	v_pk_fma_f32 v[248:249], v[66:67], v[192:193], v[248:249] op_sel:[0,0,0] op_sel_hi:[1,0,1]
	v_pk_fma_f32 v[250:251], v[76:77], v[192:193], v[250:251] op_sel:[0,0,0] op_sel_hi:[1,0,1]
	v_pk_fma_f32 v[244:245], v[52:53], v[188:189], v[244:245] op_sel:[0,1,0] op_sel_hi:[1,1,1]
	v_pk_fma_f32 v[246:247], v[10:11], v[188:189], v[246:247] op_sel:[0,1,0] op_sel_hi:[1,1,1]
	v_pk_fma_f32 v[248:249], v[68:69], v[192:193], v[248:249] op_sel:[0,1,0] op_sel_hi:[1,1,1]
	v_pk_fma_f32 v[250:251], v[78:79], v[192:193], v[250:251] op_sel:[0,1,0] op_sel_hi:[1,1,1]
	v_pk_add_f32 v[252:253], v[252:253], v[244:245]
	v_pk_add_f32 v[158:159], v[158:159], v[246:247]
	v_pk_add_f32 v[252:253], v[252:253], v[248:249]
	v_pk_add_f32 v[158:159], v[158:159], v[250:251]
	s_or_b32 s101, s2, 2
	s_mov_b32 m0, s101
	v_add_f32_dpp v252, v252, v252 quad_perm:[1,0,3,2] row_mask:0xf bank_mask:0xf bound_ctrl:1
	v_add_f32_dpp v253, v253, v253 quad_perm:[1,0,3,2] row_mask:0xf bank_mask:0xf bound_ctrl:1
	v_add_f32_dpp v158, v158, v158 quad_perm:[1,0,3,2] row_mask:0xf bank_mask:0xf bound_ctrl:1
	v_add_f32_dpp v159, v159, v159 quad_perm:[1,0,3,2] row_mask:0xf bank_mask:0xf bound_ctrl:1
	v_add_f32_dpp v252, v252, v252 quad_perm:[2,3,0,1] row_mask:0xf bank_mask:0xf bound_ctrl:1
	v_add_f32_dpp v253, v253, v253 quad_perm:[2,3,0,1] row_mask:0xf bank_mask:0xf bound_ctrl:1
	v_add_f32_dpp v158, v158, v158 quad_perm:[2,3,0,1] row_mask:0xf bank_mask:0xf bound_ctrl:1
	v_add_f32_dpp v159, v159, v159 quad_perm:[2,3,0,1] row_mask:0xf bank_mask:0xf bound_ctrl:1
	v_add_f32_dpp v252, v252, v252 row_half_mirror row_mask:0xf bank_mask:0xf bound_ctrl:1
	v_add_f32_dpp v253, v253, v253 row_half_mirror row_mask:0xf bank_mask:0xf bound_ctrl:1
	v_add_f32_dpp v158, v158, v158 row_half_mirror row_mask:0xf bank_mask:0xf bound_ctrl:1
	v_add_f32_dpp v159, v159, v159 row_half_mirror row_mask:0xf bank_mask:0xf bound_ctrl:1
	v_add_f32_dpp v252, v252, v252 row_mirror row_mask:0xf bank_mask:0xf bound_ctrl:1
	v_add_f32_dpp v253, v253, v253 row_mirror row_mask:0xf bank_mask:0xf bound_ctrl:1
	v_add_f32_dpp v158, v158, v158 row_mirror row_mask:0xf bank_mask:0xf bound_ctrl:1
	v_add_f32_dpp v159, v159, v159 row_mirror row_mask:0xf bank_mask:0xf bound_ctrl:1
	v_mov_b32_e32 v94, v252
	s_waitcnt lgkmcnt(2)
; DEVI void phase_p7(const int TIDX, const int BIDX, const int GDIM, KAP KA, unsigned char* WSB, float* OUTB, int l, unsigned char* smem) {
;     ...
; #pragma unroll 4
;       for (int c = 0; c < 36; ++c) {
;         float4 wv[4];
; #pragma unroll
;         for (int j = 0; j < 4; ++j) wv[j] = *(const float4*)(WR + c * 1024 + j * 256 + lane * 4);
; #pragma unroll
;         for (int t = 0; t < 4; ++t) {
;           float s = 0.f;
; #pragma unroll
;           for (int j = 0; j < 4; ++j) s += v[t][j].x * wv[j].x + v[t][j].y * wv[j].y + v[t][j].z * wv[j].z + v[t][j].w * wv[j].w;
;           s = wave_sum(s);
;           if (lane == c) mine[t] = s;
	v_pk_mul_f32 v[244:245], v[26:27], v[196:197] op_sel:[0,1] op_sel_hi:[1,1]
	v_mov_b32_dpp v94, v253 row_shr:4 row_mask:0xf bank_mask:0x2
	v_pk_mul_f32 v[246:247], v[4:5], v[196:197] op_sel:[0,1] op_sel_hi:[1,1]
	v_pk_mul_f32 v[248:249], v[56:57], v[200:201] op_sel:[0,1] op_sel_hi:[1,1]
	v_mov_b32_dpp v94, v158 row_shr:8 row_mask:0xf bank_mask:0x4
	v_pk_mul_f32 v[250:251], v[20:21], v[200:201] op_sel:[0,1] op_sel_hi:[1,1]
	v_pk_fma_f32 v[244:245], v[24:25], v[196:197], v[244:245] op_sel:[0,0,0] op_sel_hi:[1,0,1]
	v_mov_b32_dpp v94, v159 row_shr:12 row_mask:0xf bank_mask:0x8
	v_mov_b32_e32 v95, v94
	v_pk_fma_f32 v[246:247], v[16:17], v[196:197], v[246:247] op_sel:[0,0,0] op_sel_hi:[1,0,1]
	v_pk_fma_f32 v[248:249], v[54:55], v[200:201], v[248:249] op_sel:[0,0,0] op_sel_hi:[1,0,1]
	v_permlane16_swap_b32_e32 v94, v95
	v_pk_fma_f32 v[250:251], v[14:15], v[200:201], v[250:251] op_sel:[0,0,0] op_sel_hi:[1,0,1]
	v_add_f32_e32 v96, v94, v95
	v_mov_b32_e32 v97, v96
	v_pk_fma_f32 v[244:245], v[28:29], v[198:199], v[244:245] op_sel:[0,0,0] op_sel_hi:[1,0,1]
	v_pk_fma_f32 v[246:247], v[18:19], v[198:199], v[246:247] op_sel:[0,0,0] op_sel_hi:[1,0,1]
	v_permlane32_swap_b32_e32 v96, v97
	v_pk_fma_f32 v[248:249], v[58:59], v[202:203], v[248:249] op_sel:[0,0,0] op_sel_hi:[1,0,1]
	v_add_f32_e32 v98, v96, v97
	v_pk_fma_f32 v[250:251], v[22:23], v[202:203], v[250:251] op_sel:[0,0,0] op_sel_hi:[1,0,1]
	v_readlane_b32 s24, v98, 0
	v_readlane_b32 s25, v98, 4
	v_readlane_b32 s26, v98, 8
	v_readlane_b32 s27, v98, 12
	v_writelane_b32 v82, s24, m0
	v_writelane_b32 v33, s25, m0
	v_writelane_b32 v0, s26, m0
	v_writelane_b32 v1, s27, m0
	v_pk_fma_f32 v[244:245], v[30:31], v[198:199], v[244:245] op_sel:[0,1,0] op_sel_hi:[1,1,1]
	v_pk_fma_f32 v[246:247], v[2:3], v[198:199], v[246:247] op_sel:[0,1,0] op_sel_hi:[1,1,1]
	v_pk_fma_f32 v[248:249], v[60:61], v[202:203], v[248:249] op_sel:[0,1,0] op_sel_hi:[1,1,1]
	v_pk_fma_f32 v[250:251], v[70:71], v[202:203], v[250:251] op_sel:[0,1,0] op_sel_hi:[1,1,1]
	v_pk_add_f32 v[252:253], v[244:245], 0
	v_pk_add_f32 v[158:159], v[246:247], 0
	v_pk_add_f32 v[252:253], v[252:253], v[248:249]
	v_pk_add_f32 v[158:159], v[158:159], v[250:251]
	s_waitcnt lgkmcnt(0)
	v_pk_mul_f32 v[244:245], v[48:49], v[236:237] op_sel:[0,1] op_sel_hi:[1,1]
	v_pk_mul_f32 v[246:247], v[8:9], v[236:237] op_sel:[0,1] op_sel_hi:[1,1]
	v_pk_mul_f32 v[248:249], v[64:65], v[240:241] op_sel:[0,1] op_sel_hi:[1,1]
	v_pk_mul_f32 v[250:251], v[74:75], v[240:241] op_sel:[0,1] op_sel_hi:[1,1]
	v_pk_fma_f32 v[244:245], v[46:47], v[236:237], v[244:245] op_sel:[0,0,0] op_sel_hi:[1,0,1]
	v_pk_fma_f32 v[246:247], v[6:7], v[236:237], v[246:247] op_sel:[0,0,0] op_sel_hi:[1,0,1]
	v_pk_fma_f32 v[248:249], v[62:63], v[240:241], v[248:249] op_sel:[0,0,0] op_sel_hi:[1,0,1]
	v_pk_fma_f32 v[250:251], v[72:73], v[240:241], v[250:251] op_sel:[0,0,0] op_sel_hi:[1,0,1]
	v_pk_fma_f32 v[244:245], v[50:51], v[238:239], v[244:245] op_sel:[0,0,0] op_sel_hi:[1,0,1]
	v_pk_fma_f32 v[246:247], v[12:13], v[238:239], v[246:247] op_sel:[0,0,0] op_sel_hi:[1,0,1]
	v_pk_fma_f32 v[248:249], v[66:67], v[242:243], v[248:249] op_sel:[0,0,0] op_sel_hi:[1,0,1]
	v_pk_fma_f32 v[250:251], v[76:77], v[242:243], v[250:251] op_sel:[0,0,0] op_sel_hi:[1,0,1]
	v_pk_fma_f32 v[244:245], v[52:53], v[238:239], v[244:245] op_sel:[0,1,0] op_sel_hi:[1,1,1]
	v_pk_fma_f32 v[246:247], v[10:11], v[238:239], v[246:247] op_sel:[0,1,0] op_sel_hi:[1,1,1]
	v_pk_fma_f32 v[248:249], v[68:69], v[242:243], v[248:249] op_sel:[0,1,0] op_sel_hi:[1,1,1]
	v_pk_fma_f32 v[250:251], v[78:79], v[242:243], v[250:251] op_sel:[0,1,0] op_sel_hi:[1,1,1]
	v_pk_add_f32 v[252:253], v[252:253], v[244:245]
	v_pk_add_f32 v[158:159], v[158:159], v[246:247]
	v_pk_add_f32 v[252:253], v[252:253], v[248:249]
	v_pk_add_f32 v[158:159], v[158:159], v[250:251]
	s_or_b32 s101, s2, 3
	s_mov_b32 m0, s101
	v_add_f32_dpp v252, v252, v252 quad_perm:[1,0,3,2] row_mask:0xf bank_mask:0xf bound_ctrl:1
	v_add_f32_dpp v253, v253, v253 quad_perm:[1,0,3,2] row_mask:0xf bank_mask:0xf bound_ctrl:1
	v_add_f32_dpp v158, v158, v158 quad_perm:[1,0,3,2] row_mask:0xf bank_mask:0xf bound_ctrl:1
	v_add_f32_dpp v159, v159, v159 quad_perm:[1,0,3,2] row_mask:0xf bank_mask:0xf bound_ctrl:1
	v_add_f32_dpp v252, v252, v252 quad_perm:[2,3,0,1] row_mask:0xf bank_mask:0xf bound_ctrl:1
	v_add_f32_dpp v253, v253, v253 quad_perm:[2,3,0,1] row_mask:0xf bank_mask:0xf bound_ctrl:1
	v_add_f32_dpp v158, v158, v158 quad_perm:[2,3,0,1] row_mask:0xf bank_mask:0xf bound_ctrl:1
	v_add_f32_dpp v159, v159, v159 quad_perm:[2,3,0,1] row_mask:0xf bank_mask:0xf bound_ctrl:1
	v_add_f32_dpp v252, v252, v252 row_half_mirror row_mask:0xf bank_mask:0xf bound_ctrl:1
	v_add_f32_dpp v253, v253, v253 row_half_mirror row_mask:0xf bank_mask:0xf bound_ctrl:1
	v_add_f32_dpp v158, v158, v158 row_half_mirror row_mask:0xf bank_mask:0xf bound_ctrl:1
	v_add_f32_dpp v159, v159, v159 row_half_mirror row_mask:0xf bank_mask:0xf bound_ctrl:1
	v_add_f32_dpp v252, v252, v252 row_mirror row_mask:0xf bank_mask:0xf bound_ctrl:1
	v_add_f32_dpp v253, v253, v253 row_mirror row_mask:0xf bank_mask:0xf bound_ctrl:1
	v_add_f32_dpp v158, v158, v158 row_mirror row_mask:0xf bank_mask:0xf bound_ctrl:1
	v_add_f32_dpp v159, v159, v159 row_mirror row_mask:0xf bank_mask:0xf bound_ctrl:1
	v_mov_b32_e32 v94, v252
	s_add_i32 s2, s2, 4
	s_add_u32 s0, s0, 0x4000
	v_mov_b32_dpp v94, v253 row_shr:4 row_mask:0xf bank_mask:0x2
	s_addc_u32 s1, s1, 0
	s_nop 0
	v_mov_b32_dpp v94, v158 row_shr:8 row_mask:0xf bank_mask:0x4
	s_nop 0
	s_nop 0
	v_mov_b32_dpp v94, v159 row_shr:12 row_mask:0xf bank_mask:0x8
	v_mov_b32_e32 v95, v94
	s_nop 0
	s_nop 0
	v_permlane16_swap_b32_e32 v94, v95
	s_nop 0
	v_add_f32_e32 v96, v94, v95
	v_mov_b32_e32 v97, v96
	s_nop 0
	s_nop 0
	v_permlane32_swap_b32_e32 v96, v97
	s_nop 0
	v_add_f32_e32 v98, v96, v97
	s_nop 0
	v_readlane_b32 s24, v98, 0
	v_readlane_b32 s25, v98, 4
	v_readlane_b32 s26, v98, 8
	v_readlane_b32 s27, v98, 12
	v_writelane_b32 v82, s24, m0
	v_writelane_b32 v33, s25, m0
	v_writelane_b32 v0, s26, m0
	v_writelane_b32 v1, s27, m0
	s_branch .LBB0_69
